# compress tiles: one L2 write-back per tile (by the signalling lane) instead of eight, w2 fragment loads issued together; NSA compress wait invalidates before spinning
# speedup vs baseline: 1.0335x; 1.0178x over previous
; DI char* WS(const Params&) { return *(char* const __attribute__((address_space(4)))*)(KA() + 8 * 30); }
; DI void nsa_item(const Params& p, int l_, int item, char* smraw, bool wr = true) {
;     ...
;   {
;     int* seen = (int*)(smraw + DYN_XB + 20);
;     if (*seen == 0) {
;       if (tid == 0) {
;         const int* cd = (const int*)(WS(p) + O_CNT) + 4 + l_;
;         unsigned spins = 0;
;         while (__hip_atomic_load(cd, __ATOMIC_RELAXED, __HIP_MEMORY_SCOPE_AGENT) < 32 && ++spins < (1u << 22)) __builtin_amdgcn_s_sleep(2);
;       }
;       __syncthreads();
.LBB0_538:
	v_readlane_b32 s0, v252, 48
	v_mov_b32_e32 v213, v215
	s_and_b32 s8, s20, 15
	v_mov_b32_e32 v0, s0
	ds_read_b32 v0, v0
	v_lshlrev_b32_e32 v234, 6, v145
	v_permlane32_swap_b32_e32 v215, v213
	s_waitcnt lgkmcnt(0)
	v_cmp_ne_u32_e32 vcc, 0, v0
	s_cbranch_vccnz .LBB0_554
	buffer_inv sc1
	v_cmp_eq_u32_e64 s[36:37], 0, v143
	s_and_saveexec_b64 s[2:3], s[36:37]
	s_cbranch_execz .LBB0_551
	v_readlane_b32 s4, v252, 6
	v_readlane_b32 s5, v252, 7
	s_load_dwordx2 s[4:5], s[4:5], 0xf0
	v_readlane_b32 s0, v252, 54
	v_readlane_b32 s1, v252, 55
	s_waitcnt lgkmcnt(0)
	s_add_u32 s4, s4, s0
	s_addc_u32 s5, s5, s1
	global_load_dword v0, v222, s[4:5] offset:1040 sc1
	s_add_u32 s4, s4, 0x12a0410
	s_addc_u32 s5, s5, 0
	s_waitcnt vmcnt(0)
	v_cmp_lt_i32_e32 vcc, 31, v0
	s_cbranch_vccnz .LBB0_551
	s_mov_b32 s9, 0x3ffff8
	s_branch .LBB0_543

; DI void nsa_item(const Params& p, int l_, int item, char* smraw, bool wr = true) {
;     ...
;       __syncthreads();
;       __builtin_amdgcn_fence(__ATOMIC_ACQUIRE, "agent");
;       if (tid == 0) *seen = 1;
;       __syncthreads();
.LBB0_551:
	s_or_b64 exec, exec, s[2:3]
	s_barrier
	s_waitcnt vmcnt(0)
	s_and_saveexec_b64 s[2:3], s[36:37]
	s_cbranch_execz .LBB0_553
	v_readlane_b32 s0, v252, 48
	s_nop 1
	v_mov_b32_e32 v0, s0
	ds_write_b32 v0, v223

; #define MFMA32(a, b, c) __builtin_amdgcn_mfma_f32_32x32x16_bf16((a), (b), (c), 0, 0, 0)
; DI bf16_t f2bf(float a) { return (bf16_t)(pack2(a, 0.f) & 0xffffu); }
; DI int crow(int i, int h) { return (i & 3) + 8 * (i >> 2) + 4 * h; }
; DI char* WS(const Params&) { return *(char* const __attribute__((address_space(4)))*)(KA() + 8 * 30); }
; DI void compress_tile2(const Params& p, int l_, int tix, char* smraw) {
;     ...
;   if (half == 0) {
;     f32x16 o2[2];
; #pragma unroll
;     for (int j = 0; j < 2; ++j)
; #pragma unroll
;       for (int e = 0; e < 16; ++e) o2[j][e] = 0.f;
; #pragma unroll
;     for (int s = 0; s < 8; ++s) {
;       const bf16x8 fa = *(const bf16x8*)(Hs + (w * 32 + r31) * 136 + 16 * s + 8 * h);
; #pragma unroll
;       for (int j = 0; j < 2; ++j) {
;         const bf16x8 fb = *(const bf16x8*)(w2t + (32 * j + r31) * 128 + 16 * s + 8 * h);
;         o2[j] = MFMA32(fa, fb, o2[j]);
;       }
;     }
;     bf16_t* kc = (bf16_t*)(WS(p) + O_KC); bf16_t* vct = (bf16_t*)(WS(p) + O_VCT);
; #pragma unroll
;     for (int j = 0; j < 2; ++j) {
;       const int d = 32 * j + r31;
; #pragma unroll
;       for (int e = 0; e < 16; ++e) {
;         const int m = mt * 128 + w * 32 + crow(e, h);
;         if (m < 2032) {
;           const int b = m / 254, rem = m - b * 254, n = rem >> 1, g = rem & 1;
;           if (which == 0) kc[((size_t)((b * 2 + g) * 128 + n)) * 64 + d] = f2bf(o2[j][e]);
.LBB0_666:
	s_or_b64 exec, exec, s[42:43]
	s_waitcnt lgkmcnt(0)
	s_barrier
	s_and_saveexec_b64 s[54:55], s[36:37]
	s_cbranch_execz .LBB0_813
	s_and_b64 s[2:3], s[34:35], exec
	s_mov_b32 s0, 0x1280000
	s_cselect_b32 s0, s0, 0x1284000
	v_and_b32_e32 v48, 0x60, v155
	s_add_u32 s2, s38, s0
	v_or_b32_e32 v0, v48, v154
	s_addc_u32 s3, s39, 0
	v_mul_u32_u24_e32 v2, 0x110, v0
	v_lshlrev_b32_e32 v0, 4, v68
	v_lshl_add_u64 v[10:11], s[2:3], 0, v[0:1]
	v_lshlrev_b32_e32 v34, 8, v154
	v_mov_b32_e32 v35, v1
	v_lshl_add_u64 v[44:45], v[10:11], 0, v[34:35]
	v_add3_u32 v49, 0, v2, v0
	ds_read_b128 v[6:9], v49
	ds_read_b128 v[36:39], v49 offset:32
	v_or_b32_e32 v0, 0x2000, v34
	v_lshl_add_u64 v[46:47], v[10:11], 0, v[0:1]
	global_load_dwordx4 v[70:73], v[44:45], off
	global_load_dwordx4 v[74:77], v[46:47], off
	global_load_dwordx4 v[78:81], v[44:45], off offset:32
	global_load_dwordx4 v[82:85], v[46:47], off offset:32
	global_load_dwordx4 v[86:89], v[44:45], off offset:64
	global_load_dwordx4 v[90:93], v[46:47], off offset:64
	global_load_dwordx4 v[94:97], v[44:45], off offset:96
	global_load_dwordx4 v[98:101], v[46:47], off offset:96
	global_load_dwordx4 v[102:105], v[44:45], off offset:128
	global_load_dwordx4 v[106:109], v[46:47], off offset:128
	global_load_dwordx4 v[110:113], v[44:45], off offset:160
	global_load_dwordx4 v[114:117], v[46:47], off offset:160
	global_load_dwordx4 v[118:121], v[44:45], off offset:192
	global_load_dwordx4 v[122:125], v[46:47], off offset:192
	global_load_dwordx4 v[126:129], v[44:45], off offset:224
	global_load_dwordx4 v[130:133], v[46:47], off offset:224
	v_readlane_b32 s0, v252, 6
	v_readlane_b32 s1, v252, 7
	s_mov_b64 s[2:3], s[0:1]
	v_lshlrev_b32_e32 v0, 2, v68
	v_or3_b32 v62, v0, s4, v48
	v_mul_u32_u24_e32 v0, 0x811, v62
	v_lshrrev_b32_e32 v35, 19, v0
	v_mad_i32_i24 v0, v35, s6, v62
	s_waitcnt vmcnt(15) lgkmcnt(1)
	v_mfma_f32_32x32x16_bf16 v[18:33], v[6:9], v[70:73], 0
	s_waitcnt vmcnt(13) lgkmcnt(0)
	v_mfma_f32_32x32x16_bf16 v[18:33], v[36:39], v[78:81], v[18:33]
	v_mfma_f32_32x32x16_bf16 v[2:17], v[6:9], v[74:77], 0
	s_waitcnt vmcnt(12)
	v_mfma_f32_32x32x16_bf16 v[2:17], v[36:39], v[82:85], v[2:17]
	ds_read_b128 v[36:39], v49 offset:64
	s_waitcnt vmcnt(11) lgkmcnt(0)
	v_mfma_f32_32x32x16_bf16 v[18:33], v[36:39], v[86:89], v[18:33]
	s_waitcnt vmcnt(10)
	v_mfma_f32_32x32x16_bf16 v[2:17], v[36:39], v[90:93], v[2:17]
	ds_read_b128 v[36:39], v49 offset:96
	s_waitcnt vmcnt(9) lgkmcnt(0)
	v_mfma_f32_32x32x16_bf16 v[18:33], v[36:39], v[94:97], v[18:33]
	s_waitcnt vmcnt(8)
	v_mfma_f32_32x32x16_bf16 v[2:17], v[36:39], v[98:101], v[2:17]
	ds_read_b128 v[36:39], v49 offset:128
	s_waitcnt vmcnt(7) lgkmcnt(0)
	v_mfma_f32_32x32x16_bf16 v[18:33], v[36:39], v[102:105], v[18:33]
	s_waitcnt vmcnt(6)
	v_mfma_f32_32x32x16_bf16 v[2:17], v[36:39], v[106:109], v[2:17]
	ds_read_b128 v[36:39], v49 offset:160
	s_waitcnt vmcnt(5) lgkmcnt(0)
	v_mfma_f32_32x32x16_bf16 v[18:33], v[36:39], v[110:113], v[18:33]
	s_waitcnt vmcnt(4)
	v_mfma_f32_32x32x16_bf16 v[2:17], v[36:39], v[114:117], v[2:17]
	ds_read_b128 v[36:39], v49 offset:192
	s_waitcnt vmcnt(3) lgkmcnt(0)
	v_mfma_f32_32x32x16_bf16 v[18:33], v[36:39], v[118:121], v[18:33]
	s_waitcnt vmcnt(2)
	v_mfma_f32_32x32x16_bf16 v[2:17], v[36:39], v[122:125], v[2:17]
	ds_read_b128 v[36:39], v49 offset:224
	s_waitcnt vmcnt(1) lgkmcnt(0)
	v_mfma_f32_32x32x16_bf16 v[18:33], v[36:39], v[126:129], v[18:33]
	s_load_dwordx2 s[2:3], s[2:3], 0xf0
	s_waitcnt lgkmcnt(0)
	s_add_u32 s34, s2, 0xb6a4500
	s_addc_u32 s35, s3, 0
	s_mov_b64 s[2:3], s[0:1]
	s_load_dwordx2 s[2:3], s[2:3], 0xf0
	s_nop 4
	v_cvt_pk_bf16_f32 v18, v18, s0
	s_waitcnt vmcnt(0)
	v_mfma_f32_32x32x16_bf16 v[2:17], v[36:39], v[130:133], v[2:17]
	s_waitcnt lgkmcnt(0)
	s_add_u32 s56, s2, 0xb6e4500
	v_ashrrev_i32_e32 v36, 1, v0
	s_addc_u32 s57, s3, 0
	s_mov_b64 s[2:3], -1
	s_and_b64 vcc, exec, s[12:13]
	v_ashrrev_i32_e32 v37, 31, v36
	v_lshl_or_b32 v38, v35, 15, v34
	s_cbranch_vccz .LBB0_669
	v_mov_b32_e32 v39, v1
	v_lshl_add_u64 v[40:41], s[56:57], 0, v[38:39]
	v_lshl_add_u64 v[40:41], v[36:37], 1, v[40:41]
	global_store_short v[40:41], v18, off
	s_mov_b64 s[2:3], 0

; DI int tidx() { int t = threadIdx.x; asm volatile("" : "+v"(t)); return t; }
; DI char* WS(const Params&) { return *(char* const __attribute__((address_space(4)))*)(KA() + 8 * 30); }
; DI void compress_tile2(const Params& p, int l_, int tix, char* smraw) {
;     ...
;   __builtin_amdgcn_fence(__ATOMIC_RELEASE, "agent");
;   __syncthreads();
;   if (tidx() == 0) atomicAdd((int*)(WS(p) + O_CNT) + 4 + l_, 1);
.LBB0_813:
	s_or_b64 exec, exec, s[54:55]
	v_mov_b32_e32 v0, v201
	s_waitcnt vmcnt(0)
	s_barrier
	s_nop 0
	v_cmp_eq_u32_e32 vcc, 0, v0
	s_and_saveexec_b64 s[2:3], vcc
	s_xor_b64 s[2:3], exec, s[2:3]
	s_cbranch_execz .LBB0_511
	s_mov_b64 s[4:5], exec
	v_mbcnt_lo_u32_b32 v0, s4, 0
	v_readlane_b32 s8, v252, 6
	v_mbcnt_hi_u32_b32 v0, s5, v0
	v_readlane_b32 s9, v252, 7
	v_cmp_eq_u32_e32 vcc, 0, v0
	s_and_saveexec_b64 s[6:7], vcc
	s_xor_b64 s[6:7], exec, s[6:7]
	s_cbranch_execz .LBB0_510
	buffer_wbl2 sc1
	s_waitcnt vmcnt(0)
	s_load_dwordx2 s[8:9], s[8:9], 0xf0
	v_readlane_b32 s0, v252, 54
	v_readlane_b32 s1, v252, 55
	s_waitcnt lgkmcnt(0)
	s_add_u32 s8, s8, s0
	s_addc_u32 s9, s9, s1
	s_bcnt1_i32_b64 s0, s[4:5]
	v_mov_b32_e32 v0, s0
	global_atomic_add v222, v0, s[8:9] offset:1040
	s_branch .LBB0_510
